# attention block VALU interleave budget 40 cycles per MFMA slot (was 32) with the embedded prefetch and staging
# baseline (speedup 1.0000x reference)
.LBB0_542:
	s_cmp_gt_u32 s52, s51
	s_cbranch_scc1 .Lh1_skip
	s_mul_i32 s61, s25, 0x2200
	s_and_b32 s42, s52, 2
	s_mulk_i32 s42, 0x3400
	v_add_u32_e32 v0, s42, v160
	v_add_u32_e32 v242, s61, v161
	v_add_u32_e32 v163, 0xe000, v242
	v_add_u32_e32 v242, 0xd000, v242
	ds_read_b128 v[82:85], v0 offset:13312
	ds_read_b128 v[98:101], v0 offset:19968
	ds_read_b128 v[164:167], v0 offset:13344
	ds_read_b128 v[168:171], v0 offset:20000
	ds_read2_b64 v[238:241], v242 offset0:0 offset1:2
	ds_read2_b64 v[234:237], v163 offset0:32 offset1:34
	ds_read_b128 v[172:175], v0 offset:13376
	ds_read_b128 v[176:179], v0 offset:20032
	ds_read_b128 v[180:183], v0 offset:13408
	ds_read_b128 v[184:187], v0 offset:20064
	ds_read_b128 v[188:191], v0 offset:13440
	ds_read_b128 v[192:195], v0 offset:20096
	ds_read_b128 v[196:199], v0 offset:13472
	ds_read_b128 v[220:223], v0 offset:20128
	v_exp_f32_e32 v50, v50
	v_exp_f32_e32 v51, v51
	v_exp_f32_e32 v52, v52
	v_exp_f32_e32 v53, v53
	v_exp_f32_e32 v54, v54
	v_exp_f32_e32 v55, v55
	v_exp_f32_e32 v56, v56
	v_exp_f32_e32 v57, v57
	s_waitcnt lgkmcnt(13)
	v_mfma_f32_32x32x16_bf16 v[82:97], v[82:85], v[122:125], 0
	v_cvt_pk_bf16_f32 v224, v50, v51
	v_cvt_pk_bf16_f32 v225, v52, v53
	v_cvt_pk_bf16_f32 v226, v54, v55
	v_cvt_pk_bf16_f32 v227, v56, v57
	v_exp_f32_e32 v58, v58
	v_add_f32_e32 v200, v50, v51
	v_exp_f32_e32 v59, v59
	s_waitcnt lgkmcnt(12)
	v_mfma_f32_32x32x16_bf16 v[98:113], v[98:101], v[122:125], 0
	v_exp_f32_e32 v60, v60
	v_add_f32_e32 v201, v52, v53
	v_exp_f32_e32 v61, v61
	v_exp_f32_e32 v62, v62
	v_add_f32_e32 v200, v200, v54
	v_exp_f32_e32 v63, v63
	s_add_i32 s60, s52, 3
	s_cmp_lt_u32 s60, s48
	s_cselect_b64 s[58:59], -1, 0
	s_cmp_ge_u32 s60, s48
	s_cbranch_scc1 .Lp1a_546
	s_waitcnt vmcnt(0)
	v_lshl_add_u64 v[2:3], s[54:55], 0, v[154:155]
	v_add_co_u32_e32 v2, vcc, 0xbe09000, v2
	s_nop 1
	v_addc_co_u32_e32 v3, vcc, 0, v3, vcc
	global_load_dwordx4 v[2:5], v[2:3], off
	s_and_saveexec_b64 s[42:43], s[40:41]
	s_cbranch_execz .Lp1a_545
	v_lshl_add_u64 v[10:11], s[54:55], 0, v[152:153]
	v_add_co_u32_e32 v10, vcc, 0xbe09000, v10
	s_nop 1
	v_addc_co_u32_e32 v11, vcc, 0, v11, vcc
	global_load_dwordx4 v[10:13], v[10:11], off

.Lp1a_end:
	s_waitcnt lgkmcnt(11)
	v_mfma_f32_32x32x16_bf16 v[82:97], v[164:167], v[126:129], v[82:97]
	v_add_f32_e32 v201, v201, v55
	v_exp_f32_e32 v64, v64
	v_add_f32_e32 v200, v200, v56
	v_exp_f32_e32 v65, v65
	v_add_f32_e32 v201, v201, v57
	v_cvt_pk_bf16_f32 v228, v58, v59
	v_cvt_pk_bf16_f32 v229, v60, v61
	v_cvt_pk_bf16_f32 v230, v62, v63
	s_waitcnt lgkmcnt(10)
	v_mfma_f32_32x32x16_bf16 v[98:113], v[168:171], v[126:129], v[98:113]
	ds_read2_b64 v[164:167], v242 offset0:4 offset1:6
	ds_read2_b64 v[168:171], v163 offset0:36 offset1:38
	v_cvt_pk_bf16_f32 v231, v64, v65
	v_exp_f32_e32 v66, v66
	v_add_f32_e32 v200, v200, v58
	v_exp_f32_e32 v67, v67
	v_add_f32_e32 v201, v201, v59
	s_waitcnt lgkmcnt(11)
	v_mfma_f32_32x32x16_bf16 v[18:33], v[238:241], v[224:227], v[18:33]
	v_exp_f32_e32 v68, v68
	v_add_f32_e32 v200, v200, v60
	v_exp_f32_e32 v69, v69
	v_add_f32_e32 v201, v201, v61
	v_exp_f32_e32 v70, v70
	v_add_f32_e32 v200, v200, v62
	s_waitcnt lgkmcnt(10)
	v_mfma_f32_32x32x16_bf16 v[34:49], v[234:237], v[224:227], v[34:49]
	v_exp_f32_e32 v71, v71
	v_add_f32_e32 v201, v201, v63
	v_exp_f32_e32 v72, v72
	v_add_f32_e32 v200, v200, v64
	v_exp_f32_e32 v73, v73
	v_add_f32_e32 v201, v201, v65
	s_waitcnt lgkmcnt(9)
	v_mfma_f32_32x32x16_bf16 v[82:97], v[172:175], v[134:137], v[82:97]
	v_cvt_pk_bf16_f32 v224, v66, v67
	v_cvt_pk_bf16_f32 v225, v68, v69
	v_cvt_pk_bf16_f32 v226, v70, v71
	v_cvt_pk_bf16_f32 v227, v72, v73
	v_exp_f32_e32 v74, v74
	v_add_f32_e32 v200, v200, v66
	v_exp_f32_e32 v75, v75
	v_add_f32_e32 v201, v201, v67
	s_waitcnt lgkmcnt(8)
	v_mfma_f32_32x32x16_bf16 v[98:113], v[176:179], v[134:137], v[98:113]
	ds_read2_b64 v[172:175], v242 offset0:8 offset1:10
	ds_read2_b64 v[176:179], v163 offset0:40 offset1:42
	v_exp_f32_e32 v76, v76
	v_add_f32_e32 v200, v200, v68
	v_exp_f32_e32 v77, v77
	v_add_f32_e32 v201, v201, v69
	v_exp_f32_e32 v78, v78
	s_waitcnt lgkmcnt(3)
	v_mfma_f32_32x32x16_bf16 v[18:33], v[164:167], v[228:231], v[18:33]
	v_add_f32_e32 v200, v200, v70
	v_exp_f32_e32 v79, v79
	v_add_f32_e32 v201, v201, v71
	v_exp_f32_e32 v80, v80
	v_add_f32_e32 v200, v200, v72
	v_exp_f32_e32 v81, v81
	v_add_f32_e32 v201, v201, v73
	s_waitcnt lgkmcnt(2)
	v_mfma_f32_32x32x16_bf16 v[34:49], v[168:171], v[228:231], v[34:49]
	s_waitcnt lgkmcnt(9)
	v_mfma_f32_32x32x16_bf16 v[82:97], v[180:183], v[138:141], v[82:97]
	v_cvt_pk_bf16_f32 v228, v74, v75
	v_cvt_pk_bf16_f32 v229, v76, v77
	v_cvt_pk_bf16_f32 v230, v78, v79
	v_cvt_pk_bf16_f32 v231, v80, v81
	v_add_f32_e32 v200, v200, v74
	v_add_f32_e32 v201, v201, v75
	v_add_f32_e32 v200, v200, v76
	v_add_f32_e32 v201, v201, v77
	v_add_f32_e32 v200, v200, v78
	v_add_f32_e32 v201, v201, v79
	s_waitcnt lgkmcnt(8)
	v_mfma_f32_32x32x16_bf16 v[98:113], v[184:187], v[138:141], v[98:113]
	ds_read2_b64 v[180:183], v242 offset0:12 offset1:14
	ds_read2_b64 v[184:187], v163 offset0:44 offset1:46
	v_add_f32_e32 v200, v200, v80
	v_add_f32_e32 v201, v201, v81
	v_add_f32_e32 v200, v200, v201
	v_add_f32_e32 v162, v162, v200
	s_waitcnt lgkmcnt(3)
	v_mfma_f32_32x32x16_bf16 v[18:33], v[172:175], v[224:227], v[18:33]
	s_waitcnt lgkmcnt(2)
	v_mfma_f32_32x32x16_bf16 v[34:49], v[176:179], v[224:227], v[34:49]
	s_waitcnt lgkmcnt(9)
	v_mfma_f32_32x32x16_bf16 v[82:97], v[188:191], v[142:145], v[82:97]
	s_waitcnt lgkmcnt(8)
	v_mfma_f32_32x32x16_bf16 v[98:113], v[192:195], v[142:145], v[98:113]
	s_waitcnt lgkmcnt(7)
	v_mfma_f32_32x32x16_bf16 v[82:97], v[196:199], v[146:149], v[82:97]
	s_waitcnt lgkmcnt(6)
	v_mfma_f32_32x32x16_bf16 v[98:113], v[220:223], v[146:149], v[98:113]
	s_waitcnt lgkmcnt(0)
	v_cndmask_b32_e64 v0, 0, 1, s[44:45]
	v_cmp_ne_u32_e64 s[42:43], 1, v0
	s_andn2_b64 vcc, exec, s[44:45]
	s_cbranch_vccnz .Lt1a_mid
	s_and_b32 s44, s53, 2
	s_mulk_i32 s44, 0x3400
	s_add_i32 s62, s44, 0
	v_add_u32_e32 v0, s62, v151
	s_waitcnt vmcnt(0)
	ds_write_b128 v0, v[118:121]
	s_and_saveexec_b64 s[44:45], s[40:41]
	v_add_u32_e32 v0, s62, v159
	ds_write_b128 v0, v[6:9]
	s_or_b64 exec, exec, s[44:45]

.LBB0_556:
	s_add_i32 s61, s25, 1
	s_cmp_lg_u32 s25, 2
	s_cselect_b32 s25, s61, 0
	s_andn2_b64 vcc, exec, s[44:45]
	s_waitcnt lgkmcnt(0)
	s_barrier
	s_cbranch_vccnz .LBB0_572
	s_cmp_ge_u32 s52, s51
	s_cbranch_scc1 .Lh2_skip
	s_andn2_b32 s62, 2, s52
	s_mulk_i32 s62, 0x3400
	v_add_u32_e32 v0, s62, v160
	s_mul_i32 s62, s25, 0x2200
	v_add_u32_e32 v242, s62, v161
	v_add_u32_e32 v163, 0xe000, v242
	v_add_u32_e32 v242, 0xd000, v242
	ds_read_b128 v[50:53], v0 offset:0
	ds_read_b128 v[66:69], v0 offset:6656
	ds_read_b128 v[164:167], v0 offset:32
	ds_read_b128 v[168:171], v0 offset:6688
	ds_read2_b64 v[238:241], v242 offset0:0 offset1:2
	ds_read2_b64 v[234:237], v163 offset0:32 offset1:34
	ds_read_b128 v[172:175], v0 offset:64
	ds_read_b128 v[176:179], v0 offset:6720
	ds_read_b128 v[180:183], v0 offset:96
	ds_read_b128 v[184:187], v0 offset:6752
	ds_read_b128 v[188:191], v0 offset:128
	ds_read_b128 v[192:195], v0 offset:6784
	ds_read_b128 v[196:199], v0 offset:160
	ds_read_b128 v[220:223], v0 offset:6816
	v_exp_f32_e32 v82, v82
	v_exp_f32_e32 v83, v83
	v_exp_f32_e32 v84, v84
	v_exp_f32_e32 v85, v85
	v_exp_f32_e32 v86, v86
	v_exp_f32_e32 v87, v87
	v_exp_f32_e32 v88, v88
	v_exp_f32_e32 v89, v89
	s_waitcnt lgkmcnt(13)
	v_mfma_f32_32x32x16_bf16 v[50:65], v[50:53], v[122:125], 0
	v_cvt_pk_bf16_f32 v224, v82, v83
	v_cvt_pk_bf16_f32 v225, v84, v85
	v_cvt_pk_bf16_f32 v226, v86, v87
	v_cvt_pk_bf16_f32 v227, v88, v89
	v_exp_f32_e32 v90, v90
	v_add_f32_e32 v200, v82, v83
	v_exp_f32_e32 v91, v91
	s_waitcnt lgkmcnt(12)
	v_mfma_f32_32x32x16_bf16 v[66:81], v[66:69], v[122:125], 0
	v_exp_f32_e32 v92, v92
	v_add_f32_e32 v201, v84, v85
	v_exp_f32_e32 v93, v93
	v_exp_f32_e32 v94, v94
	v_add_f32_e32 v200, v200, v86
	v_exp_f32_e32 v95, v95
	s_cmp_ge_u32 s52, s5
	s_cbranch_scc1 .Lp2a_561
	s_waitcnt vmcnt(0)
	v_lshl_add_u64 v[118:119], s[54:55], 0, v[154:155]
	v_add_co_u32_e32 v118, vcc, 0xbe0c000, v118
	s_nop 1
	v_addc_co_u32_e32 v119, vcc, 0, v119, vcc
	global_load_dwordx4 v[118:121], v[118:119], off
	s_and_saveexec_b64 s[44:45], s[40:41]
	s_cbranch_execz .Lp2a_560
	v_lshl_add_u64 v[6:7], s[54:55], 0, v[152:153]
	v_add_co_u32_e32 v6, vcc, 0xbe0c000, v6
	s_nop 1
	v_addc_co_u32_e32 v7, vcc, 0, v7, vcc
	global_load_dwordx4 v[6:9], v[6:7], off

.Lp2a_end:
	s_waitcnt lgkmcnt(11)
	v_mfma_f32_32x32x16_bf16 v[50:65], v[164:167], v[126:129], v[50:65]
	v_add_f32_e32 v201, v201, v87
	v_exp_f32_e32 v96, v96
	v_add_f32_e32 v200, v200, v88
	v_exp_f32_e32 v97, v97
	v_add_f32_e32 v201, v201, v89
	v_cvt_pk_bf16_f32 v228, v90, v91
	v_cvt_pk_bf16_f32 v229, v92, v93
	v_cvt_pk_bf16_f32 v230, v94, v95
	s_waitcnt lgkmcnt(10)
	v_mfma_f32_32x32x16_bf16 v[66:81], v[168:171], v[126:129], v[66:81]
	ds_read2_b64 v[164:167], v242 offset0:4 offset1:6
	ds_read2_b64 v[168:171], v163 offset0:36 offset1:38
	v_cvt_pk_bf16_f32 v231, v96, v97
	v_exp_f32_e32 v98, v98
	v_add_f32_e32 v200, v200, v90
	v_exp_f32_e32 v99, v99
	v_add_f32_e32 v201, v201, v91
	s_waitcnt lgkmcnt(11)
	v_mfma_f32_32x32x16_bf16 v[18:33], v[238:241], v[224:227], v[18:33]
	v_exp_f32_e32 v100, v100
	v_add_f32_e32 v200, v200, v92
	v_exp_f32_e32 v101, v101
	v_add_f32_e32 v201, v201, v93
	v_exp_f32_e32 v102, v102
	v_add_f32_e32 v200, v200, v94
	s_waitcnt lgkmcnt(10)
	v_mfma_f32_32x32x16_bf16 v[34:49], v[234:237], v[224:227], v[34:49]
	v_exp_f32_e32 v103, v103
	v_add_f32_e32 v201, v201, v95
	v_exp_f32_e32 v104, v104
	v_add_f32_e32 v200, v200, v96
	v_exp_f32_e32 v105, v105
	v_add_f32_e32 v201, v201, v97
	s_waitcnt lgkmcnt(9)
	v_mfma_f32_32x32x16_bf16 v[50:65], v[172:175], v[134:137], v[50:65]
	v_cvt_pk_bf16_f32 v224, v98, v99
	v_cvt_pk_bf16_f32 v225, v100, v101
	v_cvt_pk_bf16_f32 v226, v102, v103
	v_cvt_pk_bf16_f32 v227, v104, v105
	v_exp_f32_e32 v106, v106
	v_add_f32_e32 v200, v200, v98
	v_exp_f32_e32 v107, v107
	v_add_f32_e32 v201, v201, v99
	s_waitcnt lgkmcnt(8)
	v_mfma_f32_32x32x16_bf16 v[66:81], v[176:179], v[134:137], v[66:81]
	ds_read2_b64 v[172:175], v242 offset0:8 offset1:10
	ds_read2_b64 v[176:179], v163 offset0:40 offset1:42
	v_exp_f32_e32 v108, v108
	v_add_f32_e32 v200, v200, v100
	v_exp_f32_e32 v109, v109
	v_add_f32_e32 v201, v201, v101
	v_exp_f32_e32 v110, v110
	s_waitcnt lgkmcnt(3)
	v_mfma_f32_32x32x16_bf16 v[18:33], v[164:167], v[228:231], v[18:33]
	v_add_f32_e32 v200, v200, v102
	v_exp_f32_e32 v111, v111
	v_add_f32_e32 v201, v201, v103
	v_exp_f32_e32 v112, v112
	v_add_f32_e32 v200, v200, v104
	v_exp_f32_e32 v113, v113
	v_add_f32_e32 v201, v201, v105
	s_waitcnt lgkmcnt(2)
	v_mfma_f32_32x32x16_bf16 v[34:49], v[168:171], v[228:231], v[34:49]
	s_waitcnt lgkmcnt(9)
	v_mfma_f32_32x32x16_bf16 v[50:65], v[180:183], v[138:141], v[50:65]
	v_cvt_pk_bf16_f32 v228, v106, v107
	v_cvt_pk_bf16_f32 v229, v108, v109
	v_cvt_pk_bf16_f32 v230, v110, v111
	v_cvt_pk_bf16_f32 v231, v112, v113
	v_add_f32_e32 v200, v200, v106
	v_add_f32_e32 v201, v201, v107
	v_add_f32_e32 v200, v200, v108
	v_add_f32_e32 v201, v201, v109
	v_add_f32_e32 v200, v200, v110
	v_add_f32_e32 v201, v201, v111
	s_waitcnt lgkmcnt(8)
	v_mfma_f32_32x32x16_bf16 v[66:81], v[184:187], v[138:141], v[66:81]
	ds_read2_b64 v[180:183], v242 offset0:12 offset1:14
	ds_read2_b64 v[184:187], v163 offset0:44 offset1:46
	v_add_f32_e32 v200, v200, v112
	v_add_f32_e32 v201, v201, v113
	v_add_f32_e32 v200, v200, v201
	v_add_f32_e32 v162, v162, v200
	s_waitcnt lgkmcnt(3)
	v_mfma_f32_32x32x16_bf16 v[18:33], v[172:175], v[224:227], v[18:33]
	s_waitcnt lgkmcnt(2)
	v_mfma_f32_32x32x16_bf16 v[34:49], v[176:179], v[224:227], v[34:49]
	s_waitcnt lgkmcnt(9)
	v_mfma_f32_32x32x16_bf16 v[50:65], v[188:191], v[142:145], v[50:65]
	s_waitcnt lgkmcnt(8)
	v_mfma_f32_32x32x16_bf16 v[66:81], v[192:195], v[142:145], v[66:81]
	s_waitcnt lgkmcnt(7)
	v_mfma_f32_32x32x16_bf16 v[50:65], v[196:199], v[146:149], v[50:65]
	s_waitcnt lgkmcnt(6)
	v_mfma_f32_32x32x16_bf16 v[66:81], v[220:223], v[146:149], v[66:81]
	s_waitcnt lgkmcnt(0)
	s_mul_i32 s58, s25, 0x2200
	s_and_b64 vcc, exec, s[44:45]
	s_cbranch_vccnz .Lt2a_mid
	s_and_b32 s44, s60, 3
	s_mulk_i32 s44, 0x3400
	s_add_i32 s52, s44, 0
	v_add_u32_e32 v0, s52, v151
	s_waitcnt vmcnt(0)
	ds_write_b128 v0, v[2:5]
	s_and_saveexec_b64 s[44:45], s[40:41]
	v_add_u32_e32 v0, s52, v159
	ds_write_b128 v0, v[10:13]
	s_or_b64 exec, exec, s[44:45]
